# GEMM K-loops: loop counter / pointer SALU moved ahead of the loop-back barrier (back-edge work off the post-barrier path)
# baseline (speedup 1.0000x reference)
.LBB0_144:
	v_add_u32_e32 v158, s84, v222
	ds_read_b128 v[130:133], v225
	ds_read_b128 v[134:137], v225 offset:1024
	ds_read_b128 v[138:141], v225 offset:2048
	ds_read_b128 v[142:145], v225 offset:3072
	ds_read_b128 v[146:149], v158
	ds_read_b128 v[150:153], v158 offset:1024
	ds_read_b128 v[154:157], v158 offset:2048
	ds_read_b128 v[158:161], v158 offset:3072
	s_add_u32 s12, s8, 0xfffc0080
	s_addc_u32 s13, s9, -1
	s_cmp_eq_u32 s62, 12
	s_cselect_b32 s15, s11, s13
	s_cselect_b32 s14, s26, s12
	s_cselect_b32 s13, s47, s61
	s_cselect_b32 s12, s49, s60
	v_lshl_add_u64 v[216:217], s[8:9], 0, v[200:201]
	s_add_i32 m0, s25, 0xc000
	ds_read_b128 v[162:165], v223
	ds_read_b128 v[208:211], v223 offset:1024
	ds_read_b128 v[212:215], v223 offset:2048
	ds_read_b128 v[226:229], v223 offset:3072
	ds_read_b128 v[230:233], v223 offset:4096
	ds_read_b128 v[234:237], v223 offset:5120
	ds_read_b128 v[238:241], v223 offset:6144
	ds_read_b128 v[242:245], v223 offset:7168
	global_load_lds_dwordx4 v[216:217], off
	v_lshl_add_u64 v[216:217], s[8:9], 0, v[202:203]
	s_add_i32 m0, s25, 0xe000
	s_nop 0
	global_load_lds_dwordx4 v[216:217], off
	s_waitcnt vmcnt(8)
	s_waitcnt lgkmcnt(0)
	s_barrier
	s_setprio 1
	s_waitcnt lgkmcnt(0)
	v_mfma_f32_16x16x32_bf16 v[126:129], v[130:133], v[162:165], v[126:129]
	v_mfma_f32_16x16x32_bf16 v[122:125], v[138:141], v[162:165], v[122:125]
	v_mfma_f32_16x16x32_bf16 v[110:113], v[130:133], v[212:215], v[110:113]
	v_mfma_f32_16x16x32_bf16 v[106:109], v[138:141], v[212:215], v[106:109]
	v_mfma_f32_16x16x32_bf16 v[94:97], v[130:133], v[230:233], v[94:97]
	v_mfma_f32_16x16x32_bf16 v[90:93], v[138:141], v[230:233], v[90:93]
	v_mfma_f32_16x16x32_bf16 v[78:81], v[130:133], v[238:241], v[78:81]
	v_mfma_f32_16x16x32_bf16 v[74:77], v[138:141], v[238:241], v[74:77]
	v_mfma_f32_16x16x32_bf16 v[126:129], v[134:137], v[208:211], v[126:129]
	v_mfma_f32_16x16x32_bf16 v[122:125], v[142:145], v[208:211], v[122:125]
	v_mfma_f32_16x16x32_bf16 v[110:113], v[134:137], v[226:229], v[110:113]
	v_mfma_f32_16x16x32_bf16 v[106:109], v[142:145], v[226:229], v[106:109]
	v_mfma_f32_16x16x32_bf16 v[94:97], v[134:137], v[234:237], v[94:97]
	v_mfma_f32_16x16x32_bf16 v[90:93], v[142:145], v[234:237], v[90:93]
	v_mfma_f32_16x16x32_bf16 v[78:81], v[134:137], v[242:245], v[78:81]
	v_mfma_f32_16x16x32_bf16 v[74:77], v[142:145], v[242:245], v[74:77]
	s_setprio 0
	s_setprio 1
	v_mfma_f32_16x16x32_bf16 v[118:121], v[146:149], v[162:165], v[118:121]
	v_mfma_f32_16x16x32_bf16 v[114:117], v[154:157], v[162:165], v[114:117]
	v_mfma_f32_16x16x32_bf16 v[102:105], v[146:149], v[212:215], v[102:105]
	v_mfma_f32_16x16x32_bf16 v[98:101], v[154:157], v[212:215], v[98:101]
	v_mfma_f32_16x16x32_bf16 v[86:89], v[146:149], v[230:233], v[86:89]
	v_mfma_f32_16x16x32_bf16 v[82:85], v[154:157], v[230:233], v[82:85]
	v_mfma_f32_16x16x32_bf16 v[70:73], v[146:149], v[238:241], v[70:73]
	v_mfma_f32_16x16x32_bf16 v[66:69], v[154:157], v[238:241], v[66:69]
	v_mfma_f32_16x16x32_bf16 v[118:121], v[150:153], v[208:211], v[118:121]
	v_mfma_f32_16x16x32_bf16 v[114:117], v[158:161], v[208:211], v[114:117]
	v_mfma_f32_16x16x32_bf16 v[102:105], v[150:153], v[226:229], v[102:105]
	v_mfma_f32_16x16x32_bf16 v[98:101], v[158:161], v[226:229], v[98:101]
	v_mfma_f32_16x16x32_bf16 v[86:89], v[150:153], v[234:237], v[86:89]
	v_mfma_f32_16x16x32_bf16 v[82:85], v[158:161], v[234:237], v[82:85]
	v_mfma_f32_16x16x32_bf16 v[70:73], v[150:153], v[242:245], v[70:73]
	v_mfma_f32_16x16x32_bf16 v[66:69], v[158:161], v[242:245], v[66:69]
	s_setprio 0
	s_barrier
	s_add_i32 s54, s83, s72
	v_lshl_add_u64 v[216:217], s[12:13], 0, v[168:169]
	s_mov_b32 m0, s54
	ds_read_b128 v[162:165], v223 offset:16384
	ds_read_b128 v[208:211], v223 offset:17408
	ds_read_b128 v[212:215], v223 offset:18432
	ds_read_b128 v[226:229], v223 offset:19456
	ds_read_b128 v[230:233], v223 offset:20480
	ds_read_b128 v[234:237], v223 offset:21504
	ds_read_b128 v[238:241], v223 offset:22528
	ds_read_b128 v[242:245], v223 offset:23552
	global_load_lds_dwordx4 v[216:217], off
	s_add_i32 m0, s54, 0x2000
	s_add_u32 s56, s12, 0x40000
	v_lshl_add_u64 v[246:247], s[12:13], 0, v[172:173]
	s_addc_u32 s57, s13, 0
	s_add_i32 s54, s84, s72
	global_load_lds_dwordx4 v[246:247], off
	v_lshl_add_u64 v[248:249], s[56:57], 0, v[168:169]
	s_mov_b32 m0, s54
	v_lshl_add_u64 v[250:251], s[14:15], 0, v[170:171]
	global_load_lds_dwordx4 v[248:249], off
	v_lshl_add_u64 v[248:249], s[56:57], 0, v[172:173]
	s_add_i32 m0, s54, 0x2000
	s_nop 0
	global_load_lds_dwordx4 v[248:249], off
	v_lshl_add_u64 v[248:249], s[14:15], 0, v[166:167]
	s_mov_b32 m0, s25
	s_nop 0
	global_load_lds_dwordx4 v[248:249], off
	s_mov_b32 m0, s73
	s_nop 0
	global_load_lds_dwordx4 v[250:251], off
	s_waitcnt vmcnt(8)
	s_waitcnt lgkmcnt(0)
	s_barrier
	s_setprio 1
	s_waitcnt lgkmcnt(0)
	v_mfma_f32_16x16x32_bf16 v[62:65], v[130:133], v[162:165], v[62:65]
	v_mfma_f32_16x16x32_bf16 v[58:61], v[138:141], v[162:165], v[58:61]
	v_mfma_f32_16x16x32_bf16 v[46:49], v[130:133], v[212:215], v[46:49]
	v_mfma_f32_16x16x32_bf16 v[42:45], v[138:141], v[212:215], v[42:45]
	v_mfma_f32_16x16x32_bf16 v[30:33], v[130:133], v[230:233], v[30:33]
	v_mfma_f32_16x16x32_bf16 v[26:29], v[138:141], v[230:233], v[26:29]
	v_mfma_f32_16x16x32_bf16 v[14:17], v[130:133], v[238:241], v[14:17]
	v_mfma_f32_16x16x32_bf16 v[10:13], v[138:141], v[238:241], v[10:13]
	v_mfma_f32_16x16x32_bf16 v[62:65], v[134:137], v[208:211], v[62:65]
	v_mfma_f32_16x16x32_bf16 v[58:61], v[142:145], v[208:211], v[58:61]
	v_mfma_f32_16x16x32_bf16 v[46:49], v[134:137], v[226:229], v[46:49]
	v_mfma_f32_16x16x32_bf16 v[42:45], v[142:145], v[226:229], v[42:45]
	v_mfma_f32_16x16x32_bf16 v[30:33], v[134:137], v[234:237], v[30:33]
	v_mfma_f32_16x16x32_bf16 v[26:29], v[142:145], v[234:237], v[26:29]
	v_mfma_f32_16x16x32_bf16 v[14:17], v[134:137], v[242:245], v[14:17]
	v_mfma_f32_16x16x32_bf16 v[10:13], v[142:145], v[242:245], v[10:13]
	s_setprio 0
	s_setprio 1
	v_mfma_f32_16x16x32_bf16 v[54:57], v[146:149], v[162:165], v[54:57]
	v_mfma_f32_16x16x32_bf16 v[50:53], v[154:157], v[162:165], v[50:53]
	v_mfma_f32_16x16x32_bf16 v[38:41], v[146:149], v[212:215], v[38:41]
	v_mfma_f32_16x16x32_bf16 v[34:37], v[154:157], v[212:215], v[34:37]
	v_mfma_f32_16x16x32_bf16 v[22:25], v[146:149], v[230:233], v[22:25]
	v_mfma_f32_16x16x32_bf16 v[18:21], v[154:157], v[230:233], v[18:21]
	v_mfma_f32_16x16x32_bf16 v[6:9], v[146:149], v[238:241], v[6:9]
	v_mfma_f32_16x16x32_bf16 v[2:5], v[154:157], v[238:241], v[2:5]
	v_mfma_f32_16x16x32_bf16 v[54:57], v[150:153], v[208:211], v[54:57]
	v_mfma_f32_16x16x32_bf16 v[50:53], v[158:161], v[208:211], v[50:53]
	v_mfma_f32_16x16x32_bf16 v[38:41], v[150:153], v[226:229], v[38:41]
	v_mfma_f32_16x16x32_bf16 v[34:37], v[158:161], v[226:229], v[34:37]
	v_mfma_f32_16x16x32_bf16 v[22:25], v[150:153], v[234:237], v[22:25]
	v_mfma_f32_16x16x32_bf16 v[18:21], v[158:161], v[234:237], v[18:21]
	v_mfma_f32_16x16x32_bf16 v[6:9], v[150:153], v[242:245], v[6:9]
	v_mfma_f32_16x16x32_bf16 v[2:5], v[158:161], v[242:245], v[2:5]
	s_setprio 0
	s_barrier
	s_add_i32 s54, 0, 0x18000
	s_add_i32 s55, 0, 0x1c000
	v_add_u32_e32 v142, s54, v222
	v_add_u32_e32 v158, s55, v222
	ds_read_b128 v[130:133], v142
	ds_read_b128 v[134:137], v142 offset:1024
	ds_read_b128 v[138:141], v142 offset:2048
	ds_read_b128 v[142:145], v142 offset:3072
	ds_read_b128 v[146:149], v158
	ds_read_b128 v[150:153], v158 offset:1024
	ds_read_b128 v[154:157], v158 offset:2048
	ds_read_b128 v[158:161], v158 offset:3072
	s_add_u32 s14, s14, 0x40000
	s_addc_u32 s15, s15, 0
	s_mov_b32 m0, s74
	v_lshl_add_u64 v[252:253], s[14:15], 0, v[166:167]
	ds_read_b128 v[162:165], v223 offset:32768
	ds_read_b128 v[208:211], v223 offset:33792
	ds_read_b128 v[212:215], v223 offset:34816
	ds_read_b128 v[226:229], v223 offset:35840
	ds_read_b128 v[230:233], v223 offset:36864
	ds_read_b128 v[234:237], v223 offset:37888
	ds_read_b128 v[238:241], v223 offset:38912
	ds_read_b128 v[242:245], v223 offset:39936
	global_load_lds_dwordx4 v[252:253], off
	v_lshl_add_u64 v[252:253], s[14:15], 0, v[170:171]
	s_mov_b32 m0, s75
	s_nop 0
	global_load_lds_dwordx4 v[252:253], off
	s_waitcnt vmcnt(8)
	s_waitcnt lgkmcnt(0)
	s_barrier
	s_setprio 1
	s_waitcnt lgkmcnt(0)
	v_mfma_f32_16x16x32_bf16 v[126:129], v[130:133], v[162:165], v[126:129]
	v_mfma_f32_16x16x32_bf16 v[122:125], v[138:141], v[162:165], v[122:125]
	v_mfma_f32_16x16x32_bf16 v[110:113], v[130:133], v[212:215], v[110:113]
	v_mfma_f32_16x16x32_bf16 v[106:109], v[138:141], v[212:215], v[106:109]
	v_mfma_f32_16x16x32_bf16 v[94:97], v[130:133], v[230:233], v[94:97]
	v_mfma_f32_16x16x32_bf16 v[90:93], v[138:141], v[230:233], v[90:93]
	v_mfma_f32_16x16x32_bf16 v[78:81], v[130:133], v[238:241], v[78:81]
	v_mfma_f32_16x16x32_bf16 v[74:77], v[138:141], v[238:241], v[74:77]
	v_mfma_f32_16x16x32_bf16 v[126:129], v[134:137], v[208:211], v[126:129]
	v_mfma_f32_16x16x32_bf16 v[122:125], v[142:145], v[208:211], v[122:125]
	v_mfma_f32_16x16x32_bf16 v[110:113], v[134:137], v[226:229], v[110:113]
	v_mfma_f32_16x16x32_bf16 v[106:109], v[142:145], v[226:229], v[106:109]
	v_mfma_f32_16x16x32_bf16 v[94:97], v[134:137], v[234:237], v[94:97]
	v_mfma_f32_16x16x32_bf16 v[90:93], v[142:145], v[234:237], v[90:93]
	v_mfma_f32_16x16x32_bf16 v[78:81], v[134:137], v[242:245], v[78:81]
	v_mfma_f32_16x16x32_bf16 v[74:77], v[142:145], v[242:245], v[74:77]
	s_setprio 0
	s_setprio 1
	v_mfma_f32_16x16x32_bf16 v[118:121], v[146:149], v[162:165], v[118:121]
	v_mfma_f32_16x16x32_bf16 v[114:117], v[154:157], v[162:165], v[114:117]
	v_mfma_f32_16x16x32_bf16 v[102:105], v[146:149], v[212:215], v[102:105]
	v_mfma_f32_16x16x32_bf16 v[98:101], v[154:157], v[212:215], v[98:101]
	v_mfma_f32_16x16x32_bf16 v[86:89], v[146:149], v[230:233], v[86:89]
	v_mfma_f32_16x16x32_bf16 v[82:85], v[154:157], v[230:233], v[82:85]
	v_mfma_f32_16x16x32_bf16 v[70:73], v[146:149], v[238:241], v[70:73]
	v_mfma_f32_16x16x32_bf16 v[66:69], v[154:157], v[238:241], v[66:69]
	v_mfma_f32_16x16x32_bf16 v[118:121], v[150:153], v[208:211], v[118:121]
	v_mfma_f32_16x16x32_bf16 v[114:117], v[158:161], v[208:211], v[114:117]
	v_mfma_f32_16x16x32_bf16 v[102:105], v[150:153], v[226:229], v[102:105]
	v_mfma_f32_16x16x32_bf16 v[98:101], v[158:161], v[226:229], v[98:101]
	v_mfma_f32_16x16x32_bf16 v[86:89], v[150:153], v[234:237], v[86:89]
	v_mfma_f32_16x16x32_bf16 v[82:85], v[158:161], v[234:237], v[82:85]
	v_mfma_f32_16x16x32_bf16 v[70:73], v[150:153], v[242:245], v[70:73]
	v_mfma_f32_16x16x32_bf16 v[66:69], v[158:161], v[242:245], v[66:69]
	s_setprio 0
	s_barrier
	s_add_i32 s14, s54, s72
	v_lshl_add_u64 v[216:217], v[216:217], 0, s[38:39]
	s_mov_b32 m0, s14
	ds_read_b128 v[162:165], v223 offset:49152
	ds_read_b128 v[208:211], v223 offset:50176
	ds_read_b128 v[212:215], v223 offset:51200
	ds_read_b128 v[226:229], v223 offset:52224
	ds_read_b128 v[230:233], v223 offset:53248
	ds_read_b128 v[234:237], v223 offset:54272
	ds_read_b128 v[238:241], v223 offset:55296
	ds_read_b128 v[242:245], v223 offset:56320
	global_load_lds_dwordx4 v[216:217], off
	s_add_i32 m0, s14, 0x2000
	s_add_u32 s12, s12, 0x40080
	v_lshl_add_u64 v[216:217], v[246:247], 0, s[38:39]
	s_addc_u32 s13, s13, 0
	s_add_i32 s14, s55, s72
	global_load_lds_dwordx4 v[216:217], off
	v_lshl_add_u64 v[216:217], s[12:13], 0, v[168:169]
	s_mov_b32 m0, s14
	s_nop 0
	global_load_lds_dwordx4 v[216:217], off
	v_lshl_add_u64 v[216:217], s[12:13], 0, v[172:173]
	s_add_i32 m0, s14, 0x2000
	s_nop 0
	global_load_lds_dwordx4 v[216:217], off
	v_lshl_add_u64 v[216:217], v[248:249], 0, s[38:39]
	s_mov_b32 m0, s78
	s_nop 0
	global_load_lds_dwordx4 v[216:217], off
	v_lshl_add_u64 v[216:217], v[250:251], 0, s[38:39]
	s_mov_b32 m0, s79
	s_nop 0
	global_load_lds_dwordx4 v[216:217], off
	s_waitcnt vmcnt(8)
	s_waitcnt lgkmcnt(0)
	s_barrier
	s_setprio 1
	s_waitcnt lgkmcnt(0)
	v_mfma_f32_16x16x32_bf16 v[62:65], v[130:133], v[162:165], v[62:65]
	v_mfma_f32_16x16x32_bf16 v[58:61], v[138:141], v[162:165], v[58:61]
	v_mfma_f32_16x16x32_bf16 v[46:49], v[130:133], v[212:215], v[46:49]
	v_mfma_f32_16x16x32_bf16 v[42:45], v[138:141], v[212:215], v[42:45]
	v_mfma_f32_16x16x32_bf16 v[30:33], v[130:133], v[230:233], v[30:33]
	v_mfma_f32_16x16x32_bf16 v[26:29], v[138:141], v[230:233], v[26:29]
	v_mfma_f32_16x16x32_bf16 v[14:17], v[130:133], v[238:241], v[14:17]
	v_mfma_f32_16x16x32_bf16 v[10:13], v[138:141], v[238:241], v[10:13]
	v_mfma_f32_16x16x32_bf16 v[62:65], v[134:137], v[208:211], v[62:65]
	v_mfma_f32_16x16x32_bf16 v[58:61], v[142:145], v[208:211], v[58:61]
	v_mfma_f32_16x16x32_bf16 v[46:49], v[134:137], v[226:229], v[46:49]
	v_mfma_f32_16x16x32_bf16 v[42:45], v[142:145], v[226:229], v[42:45]
	v_mfma_f32_16x16x32_bf16 v[30:33], v[134:137], v[234:237], v[30:33]
	v_mfma_f32_16x16x32_bf16 v[26:29], v[142:145], v[234:237], v[26:29]
	v_mfma_f32_16x16x32_bf16 v[14:17], v[134:137], v[242:245], v[14:17]
	v_mfma_f32_16x16x32_bf16 v[10:13], v[142:145], v[242:245], v[10:13]
	s_setprio 0
	s_setprio 1
	v_mfma_f32_16x16x32_bf16 v[54:57], v[146:149], v[162:165], v[54:57]
	v_mfma_f32_16x16x32_bf16 v[50:53], v[154:157], v[162:165], v[50:53]
	v_mfma_f32_16x16x32_bf16 v[38:41], v[146:149], v[212:215], v[38:41]
	v_mfma_f32_16x16x32_bf16 v[34:37], v[154:157], v[212:215], v[34:37]
	v_mfma_f32_16x16x32_bf16 v[22:25], v[146:149], v[230:233], v[22:25]
	v_mfma_f32_16x16x32_bf16 v[18:21], v[154:157], v[230:233], v[18:21]
	v_mfma_f32_16x16x32_bf16 v[6:9], v[146:149], v[238:241], v[6:9]
	v_mfma_f32_16x16x32_bf16 v[2:5], v[154:157], v[238:241], v[2:5]
	v_mfma_f32_16x16x32_bf16 v[54:57], v[150:153], v[208:211], v[54:57]
	v_mfma_f32_16x16x32_bf16 v[50:53], v[158:161], v[208:211], v[50:53]
	v_mfma_f32_16x16x32_bf16 v[38:41], v[150:153], v[226:229], v[38:41]
	v_mfma_f32_16x16x32_bf16 v[34:37], v[158:161], v[226:229], v[34:37]
	v_mfma_f32_16x16x32_bf16 v[22:25], v[150:153], v[234:237], v[22:25]
	v_mfma_f32_16x16x32_bf16 v[18:21], v[158:161], v[234:237], v[18:21]
	v_mfma_f32_16x16x32_bf16 v[6:9], v[150:153], v[242:245], v[6:9]
	v_mfma_f32_16x16x32_bf16 v[2:5], v[158:161], v[242:245], v[2:5]
	s_setprio 0
	s_add_i32 s62, s62, 2
	s_add_u32 s8, s8, 0x100
	s_addc_u32 s9, s9, 0
	s_add_u32 s60, s60, 0x100
	s_addc_u32 s61, s61, 0
	s_cmp_gt_u32 s62, 13
	s_barrier
	s_cbranch_scc0 .LBB0_144
	s_and_b64 vcc, exec, s[40:41]
	s_cbranch_vccz .LBB0_147
	s_barrier

.LBB0_647:
	ds_read_b128 v[154:157], v150
	ds_read_b128 v[158:161], v150 offset:1024
	ds_read_b128 v[162:165], v150 offset:2048
	ds_read_b128 v[166:169], v150 offset:3072
	ds_read_b128 v[170:173], v151
	ds_read_b128 v[174:177], v151 offset:1024
	ds_read_b128 v[178:181], v151 offset:2048
	ds_read_b128 v[186:189], v151 offset:3072
	s_add_u32 s40, s38, 0xfffc0080
	s_addc_u32 s41, s39, -1
	s_cmp_eq_u32 s74, 12
	s_cselect_b32 s43, s27, s41
	s_cselect_b32 s42, s68, s40
	s_cselect_b32 s41, s25, s73
	s_cselect_b32 s40, s69, s72
	v_lshl_add_u64 v[146:147], s[38:39], 0, v[138:139]
	s_add_i32 m0, s37, 0xc000
	ds_read_b128 v[190:193], v152
	ds_read_b128 v[194:197], v152 offset:1024
	ds_read_b128 v[198:201], v152 offset:2048
	ds_read_b128 v[202:205], v152 offset:3072
	ds_read_b128 v[206:209], v152 offset:4096
	ds_read_b128 v[210:213], v152 offset:5120
	ds_read_b128 v[214:217], v152 offset:6144
	ds_read_b128 v[218:221], v152 offset:7168
	global_load_lds_dwordx4 v[146:147], off
	v_lshl_add_u64 v[146:147], s[38:39], 0, v[140:141]
	s_add_i32 m0, s37, 0xe000
	s_nop 0
	global_load_lds_dwordx4 v[146:147], off
	s_waitcnt vmcnt(8)
	s_waitcnt lgkmcnt(0)
	s_barrier
	s_setprio 1
	s_waitcnt lgkmcnt(0)
	v_mfma_f32_16x16x32_bf16 v[126:129], v[154:157], v[190:193], v[126:129]
	v_mfma_f32_16x16x32_bf16 v[122:125], v[162:165], v[190:193], v[122:125]
	v_mfma_f32_16x16x32_bf16 v[118:121], v[154:157], v[198:201], v[118:121]
	v_mfma_f32_16x16x32_bf16 v[110:113], v[162:165], v[198:201], v[110:113]
	v_mfma_f32_16x16x32_bf16 v[102:105], v[154:157], v[206:209], v[102:105]
	v_mfma_f32_16x16x32_bf16 v[94:97], v[162:165], v[206:209], v[94:97]
	v_mfma_f32_16x16x32_bf16 v[86:89], v[154:157], v[214:217], v[86:89]
	v_mfma_f32_16x16x32_bf16 v[78:81], v[162:165], v[214:217], v[78:81]
	v_mfma_f32_16x16x32_bf16 v[126:129], v[158:161], v[194:197], v[126:129]
	v_mfma_f32_16x16x32_bf16 v[122:125], v[166:169], v[194:197], v[122:125]
	v_mfma_f32_16x16x32_bf16 v[118:121], v[158:161], v[202:205], v[118:121]
	v_mfma_f32_16x16x32_bf16 v[110:113], v[166:169], v[202:205], v[110:113]
	v_mfma_f32_16x16x32_bf16 v[102:105], v[158:161], v[210:213], v[102:105]
	v_mfma_f32_16x16x32_bf16 v[94:97], v[166:169], v[210:213], v[94:97]
	v_mfma_f32_16x16x32_bf16 v[86:89], v[158:161], v[218:221], v[86:89]
	v_mfma_f32_16x16x32_bf16 v[78:81], v[166:169], v[218:221], v[78:81]
	s_setprio 0
	s_setprio 1
	v_mfma_f32_16x16x32_bf16 v[114:117], v[170:173], v[190:193], v[114:117]
	v_mfma_f32_16x16x32_bf16 v[106:109], v[178:181], v[190:193], v[106:109]
	v_mfma_f32_16x16x32_bf16 v[98:101], v[170:173], v[198:201], v[98:101]
	v_mfma_f32_16x16x32_bf16 v[90:93], v[178:181], v[198:201], v[90:93]
	v_mfma_f32_16x16x32_bf16 v[82:85], v[170:173], v[206:209], v[82:85]
	v_mfma_f32_16x16x32_bf16 v[74:77], v[178:181], v[206:209], v[74:77]
	v_mfma_f32_16x16x32_bf16 v[70:73], v[170:173], v[214:217], v[70:73]
	v_mfma_f32_16x16x32_bf16 v[66:69], v[178:181], v[214:217], v[66:69]
	v_mfma_f32_16x16x32_bf16 v[114:117], v[174:177], v[194:197], v[114:117]
	v_mfma_f32_16x16x32_bf16 v[106:109], v[186:189], v[194:197], v[106:109]
	v_mfma_f32_16x16x32_bf16 v[98:101], v[174:177], v[202:205], v[98:101]
	v_mfma_f32_16x16x32_bf16 v[90:93], v[186:189], v[202:205], v[90:93]
	v_mfma_f32_16x16x32_bf16 v[82:85], v[174:177], v[210:213], v[82:85]
	v_mfma_f32_16x16x32_bf16 v[74:77], v[186:189], v[210:213], v[74:77]
	v_mfma_f32_16x16x32_bf16 v[70:73], v[174:177], v[218:221], v[70:73]
	v_mfma_f32_16x16x32_bf16 v[66:69], v[186:189], v[218:221], v[66:69]
	s_setprio 0
	s_barrier
	s_add_i32 s54, s60, s45
	v_lshl_add_u64 v[146:147], s[40:41], 0, v[132:133]
	s_mov_b32 m0, s54
	ds_read_b128 v[190:193], v152 offset:16384
	ds_read_b128 v[194:197], v152 offset:17408
	ds_read_b128 v[198:201], v152 offset:18432
	ds_read_b128 v[202:205], v152 offset:19456
	ds_read_b128 v[206:209], v152 offset:20480
	ds_read_b128 v[210:213], v152 offset:21504
	ds_read_b128 v[214:217], v152 offset:22528
	ds_read_b128 v[218:221], v152 offset:23552
	global_load_lds_dwordx4 v[146:147], off
	s_add_i32 m0, s54, 0x2000
	s_add_u32 s54, s40, 0x40000
	v_lshl_add_u64 v[182:183], s[40:41], 0, v[136:137]
	s_addc_u32 s55, s41, 0
	s_add_i32 s56, s61, s45
	global_load_lds_dwordx4 v[182:183], off
	v_lshl_add_u64 v[222:223], s[54:55], 0, v[132:133]
	s_mov_b32 m0, s56
	v_lshl_add_u64 v[224:225], s[42:43], 0, v[134:135]
	global_load_lds_dwordx4 v[222:223], off
	v_lshl_add_u64 v[222:223], s[54:55], 0, v[136:137]
	s_add_i32 m0, s56, 0x2000
	s_nop 0
	global_load_lds_dwordx4 v[222:223], off
	v_lshl_add_u64 v[222:223], s[42:43], 0, v[130:131]
	s_mov_b32 m0, s37
	s_nop 0
	global_load_lds_dwordx4 v[222:223], off
	s_mov_b32 m0, s47
	s_nop 0
	global_load_lds_dwordx4 v[224:225], off
	s_waitcnt vmcnt(8)
	s_waitcnt lgkmcnt(0)
	s_barrier
	s_setprio 1
	s_waitcnt lgkmcnt(0)
	v_mfma_f32_16x16x32_bf16 v[62:65], v[154:157], v[190:193], v[62:65]
	v_mfma_f32_16x16x32_bf16 v[58:61], v[162:165], v[190:193], v[58:61]
	v_mfma_f32_16x16x32_bf16 v[54:57], v[154:157], v[198:201], v[54:57]
	v_mfma_f32_16x16x32_bf16 v[46:49], v[162:165], v[198:201], v[46:49]
	v_mfma_f32_16x16x32_bf16 v[38:41], v[154:157], v[206:209], v[38:41]
	v_mfma_f32_16x16x32_bf16 v[30:33], v[162:165], v[206:209], v[30:33]
	v_mfma_f32_16x16x32_bf16 v[22:25], v[154:157], v[214:217], v[22:25]
	v_mfma_f32_16x16x32_bf16 v[14:17], v[162:165], v[214:217], v[14:17]
	v_mfma_f32_16x16x32_bf16 v[62:65], v[158:161], v[194:197], v[62:65]
	v_mfma_f32_16x16x32_bf16 v[58:61], v[166:169], v[194:197], v[58:61]
	v_mfma_f32_16x16x32_bf16 v[54:57], v[158:161], v[202:205], v[54:57]
	v_mfma_f32_16x16x32_bf16 v[46:49], v[166:169], v[202:205], v[46:49]
	v_mfma_f32_16x16x32_bf16 v[38:41], v[158:161], v[210:213], v[38:41]
	v_mfma_f32_16x16x32_bf16 v[30:33], v[166:169], v[210:213], v[30:33]
	v_mfma_f32_16x16x32_bf16 v[22:25], v[158:161], v[218:221], v[22:25]
	v_mfma_f32_16x16x32_bf16 v[14:17], v[166:169], v[218:221], v[14:17]
	s_setprio 0
	s_setprio 1
	v_mfma_f32_16x16x32_bf16 v[50:53], v[170:173], v[190:193], v[50:53]
	v_mfma_f32_16x16x32_bf16 v[42:45], v[178:181], v[190:193], v[42:45]
	v_mfma_f32_16x16x32_bf16 v[34:37], v[170:173], v[198:201], v[34:37]
	v_mfma_f32_16x16x32_bf16 v[26:29], v[178:181], v[198:201], v[26:29]
	v_mfma_f32_16x16x32_bf16 v[18:21], v[170:173], v[206:209], v[18:21]
	v_mfma_f32_16x16x32_bf16 v[10:13], v[178:181], v[206:209], v[10:13]
	v_mfma_f32_16x16x32_bf16 v[6:9], v[170:173], v[214:217], v[6:9]
	v_mfma_f32_16x16x32_bf16 v[2:5], v[178:181], v[214:217], v[2:5]
	v_mfma_f32_16x16x32_bf16 v[50:53], v[174:177], v[194:197], v[50:53]
	v_mfma_f32_16x16x32_bf16 v[42:45], v[186:189], v[194:197], v[42:45]
	v_mfma_f32_16x16x32_bf16 v[34:37], v[174:177], v[202:205], v[34:37]
	v_mfma_f32_16x16x32_bf16 v[26:29], v[186:189], v[202:205], v[26:29]
	v_mfma_f32_16x16x32_bf16 v[18:21], v[174:177], v[210:213], v[18:21]
	v_mfma_f32_16x16x32_bf16 v[10:13], v[186:189], v[210:213], v[10:13]
	v_mfma_f32_16x16x32_bf16 v[6:9], v[174:177], v[218:221], v[6:9]
	v_mfma_f32_16x16x32_bf16 v[2:5], v[186:189], v[218:221], v[2:5]
	s_setprio 0
	s_barrier
	s_add_i32 s54, 0, 0x18000
	v_add_u32_e32 v153, s54, v148
	s_add_i32 s55, 0, 0x1c000
	ds_read_b128 v[154:157], v153
	ds_read_b128 v[158:161], v153 offset:1024
	ds_read_b128 v[162:165], v153 offset:2048
	ds_read_b128 v[166:169], v153 offset:3072
	v_add_u32_e32 v153, s55, v148
	ds_read_b128 v[170:173], v153
	ds_read_b128 v[174:177], v153 offset:1024
	ds_read_b128 v[178:181], v153 offset:2048
	ds_read_b128 v[186:189], v153 offset:3072
	s_add_u32 s42, s42, 0x40000
	s_addc_u32 s43, s43, 0
	s_mov_b32 m0, s48
	v_lshl_add_u64 v[226:227], s[42:43], 0, v[130:131]
	ds_read_b128 v[190:193], v152 offset:32768
	ds_read_b128 v[194:197], v152 offset:33792
	ds_read_b128 v[198:201], v152 offset:34816
	ds_read_b128 v[202:205], v152 offset:35840
	ds_read_b128 v[206:209], v152 offset:36864
	ds_read_b128 v[210:213], v152 offset:37888
	ds_read_b128 v[214:217], v152 offset:38912
	ds_read_b128 v[218:221], v152 offset:39936
	global_load_lds_dwordx4 v[226:227], off
	v_lshl_add_u64 v[226:227], s[42:43], 0, v[134:135]
	s_mov_b32 m0, s49
	s_nop 0
	global_load_lds_dwordx4 v[226:227], off
	s_waitcnt vmcnt(8)
	s_waitcnt lgkmcnt(0)
	s_barrier
	s_setprio 1
	s_waitcnt lgkmcnt(0)
	v_mfma_f32_16x16x32_bf16 v[126:129], v[154:157], v[190:193], v[126:129]
	v_mfma_f32_16x16x32_bf16 v[122:125], v[162:165], v[190:193], v[122:125]
	v_mfma_f32_16x16x32_bf16 v[118:121], v[154:157], v[198:201], v[118:121]
	v_mfma_f32_16x16x32_bf16 v[110:113], v[162:165], v[198:201], v[110:113]
	v_mfma_f32_16x16x32_bf16 v[102:105], v[154:157], v[206:209], v[102:105]
	v_mfma_f32_16x16x32_bf16 v[94:97], v[162:165], v[206:209], v[94:97]
	v_mfma_f32_16x16x32_bf16 v[86:89], v[154:157], v[214:217], v[86:89]
	v_mfma_f32_16x16x32_bf16 v[78:81], v[162:165], v[214:217], v[78:81]
	v_mfma_f32_16x16x32_bf16 v[126:129], v[158:161], v[194:197], v[126:129]
	v_mfma_f32_16x16x32_bf16 v[122:125], v[166:169], v[194:197], v[122:125]
	v_mfma_f32_16x16x32_bf16 v[118:121], v[158:161], v[202:205], v[118:121]
	v_mfma_f32_16x16x32_bf16 v[110:113], v[166:169], v[202:205], v[110:113]
	v_mfma_f32_16x16x32_bf16 v[102:105], v[158:161], v[210:213], v[102:105]
	v_mfma_f32_16x16x32_bf16 v[94:97], v[166:169], v[210:213], v[94:97]
	v_mfma_f32_16x16x32_bf16 v[86:89], v[158:161], v[218:221], v[86:89]
	v_mfma_f32_16x16x32_bf16 v[78:81], v[166:169], v[218:221], v[78:81]
	s_setprio 0
	s_setprio 1
	v_mfma_f32_16x16x32_bf16 v[114:117], v[170:173], v[190:193], v[114:117]
	v_mfma_f32_16x16x32_bf16 v[106:109], v[178:181], v[190:193], v[106:109]
	v_mfma_f32_16x16x32_bf16 v[98:101], v[170:173], v[198:201], v[98:101]
	v_mfma_f32_16x16x32_bf16 v[90:93], v[178:181], v[198:201], v[90:93]
	v_mfma_f32_16x16x32_bf16 v[82:85], v[170:173], v[206:209], v[82:85]
	v_mfma_f32_16x16x32_bf16 v[74:77], v[178:181], v[206:209], v[74:77]
	v_mfma_f32_16x16x32_bf16 v[70:73], v[170:173], v[214:217], v[70:73]
	v_mfma_f32_16x16x32_bf16 v[66:69], v[178:181], v[214:217], v[66:69]
	v_mfma_f32_16x16x32_bf16 v[114:117], v[174:177], v[194:197], v[114:117]
	v_mfma_f32_16x16x32_bf16 v[106:109], v[186:189], v[194:197], v[106:109]
	v_mfma_f32_16x16x32_bf16 v[98:101], v[174:177], v[202:205], v[98:101]
	v_mfma_f32_16x16x32_bf16 v[90:93], v[186:189], v[202:205], v[90:93]
	v_mfma_f32_16x16x32_bf16 v[82:85], v[174:177], v[210:213], v[82:85]
	v_mfma_f32_16x16x32_bf16 v[74:77], v[186:189], v[210:213], v[74:77]
	v_mfma_f32_16x16x32_bf16 v[70:73], v[174:177], v[218:221], v[70:73]
	v_mfma_f32_16x16x32_bf16 v[66:69], v[186:189], v[218:221], v[66:69]
	s_setprio 0
	s_barrier
	s_add_i32 s42, s54, s45
	v_lshl_add_u64 v[146:147], v[146:147], 0, s[14:15]
	s_mov_b32 m0, s42
	ds_read_b128 v[190:193], v152 offset:49152
	ds_read_b128 v[194:197], v152 offset:50176
	ds_read_b128 v[198:201], v152 offset:51200
	ds_read_b128 v[202:205], v152 offset:52224
	ds_read_b128 v[206:209], v152 offset:53248
	ds_read_b128 v[210:213], v152 offset:54272
	ds_read_b128 v[214:217], v152 offset:55296
	ds_read_b128 v[218:221], v152 offset:56320
	global_load_lds_dwordx4 v[146:147], off
	s_add_i32 m0, s42, 0x2000
	s_add_u32 s40, s40, 0x40080
	v_lshl_add_u64 v[146:147], v[182:183], 0, s[14:15]
	s_addc_u32 s41, s41, 0
	s_add_i32 s42, s55, s45
	global_load_lds_dwordx4 v[146:147], off
	v_lshl_add_u64 v[146:147], s[40:41], 0, v[132:133]
	s_mov_b32 m0, s42
	s_nop 0
	global_load_lds_dwordx4 v[146:147], off
	v_lshl_add_u64 v[146:147], s[40:41], 0, v[136:137]
	s_add_i32 m0, s42, 0x2000
	s_nop 0
	global_load_lds_dwordx4 v[146:147], off
	v_lshl_add_u64 v[146:147], v[222:223], 0, s[14:15]
	s_mov_b32 m0, s58
	s_nop 0
	global_load_lds_dwordx4 v[146:147], off
	v_lshl_add_u64 v[146:147], v[224:225], 0, s[14:15]
	s_mov_b32 m0, s59
	s_nop 0
	global_load_lds_dwordx4 v[146:147], off
	s_waitcnt vmcnt(8)
	s_waitcnt lgkmcnt(0)
	s_barrier
	s_setprio 1
	s_waitcnt lgkmcnt(0)
	v_mfma_f32_16x16x32_bf16 v[62:65], v[154:157], v[190:193], v[62:65]
	v_mfma_f32_16x16x32_bf16 v[58:61], v[162:165], v[190:193], v[58:61]
	v_mfma_f32_16x16x32_bf16 v[54:57], v[154:157], v[198:201], v[54:57]
	v_mfma_f32_16x16x32_bf16 v[46:49], v[162:165], v[198:201], v[46:49]
	v_mfma_f32_16x16x32_bf16 v[38:41], v[154:157], v[206:209], v[38:41]
	v_mfma_f32_16x16x32_bf16 v[30:33], v[162:165], v[206:209], v[30:33]
	v_mfma_f32_16x16x32_bf16 v[22:25], v[154:157], v[214:217], v[22:25]
	v_mfma_f32_16x16x32_bf16 v[14:17], v[162:165], v[214:217], v[14:17]
	v_mfma_f32_16x16x32_bf16 v[62:65], v[158:161], v[194:197], v[62:65]
	v_mfma_f32_16x16x32_bf16 v[58:61], v[166:169], v[194:197], v[58:61]
	v_mfma_f32_16x16x32_bf16 v[54:57], v[158:161], v[202:205], v[54:57]
	v_mfma_f32_16x16x32_bf16 v[46:49], v[166:169], v[202:205], v[46:49]
	v_mfma_f32_16x16x32_bf16 v[38:41], v[158:161], v[210:213], v[38:41]
	v_mfma_f32_16x16x32_bf16 v[30:33], v[166:169], v[210:213], v[30:33]
	v_mfma_f32_16x16x32_bf16 v[22:25], v[158:161], v[218:221], v[22:25]
	v_mfma_f32_16x16x32_bf16 v[14:17], v[166:169], v[218:221], v[14:17]
	s_setprio 0
	s_setprio 1
	v_mfma_f32_16x16x32_bf16 v[50:53], v[170:173], v[190:193], v[50:53]
	v_mfma_f32_16x16x32_bf16 v[42:45], v[178:181], v[190:193], v[42:45]
	v_mfma_f32_16x16x32_bf16 v[34:37], v[170:173], v[198:201], v[34:37]
	v_mfma_f32_16x16x32_bf16 v[26:29], v[178:181], v[198:201], v[26:29]
	v_mfma_f32_16x16x32_bf16 v[18:21], v[170:173], v[206:209], v[18:21]
	v_mfma_f32_16x16x32_bf16 v[10:13], v[178:181], v[206:209], v[10:13]
	v_mfma_f32_16x16x32_bf16 v[6:9], v[170:173], v[214:217], v[6:9]
	v_mfma_f32_16x16x32_bf16 v[2:5], v[178:181], v[214:217], v[2:5]
	v_mfma_f32_16x16x32_bf16 v[50:53], v[174:177], v[194:197], v[50:53]
	v_mfma_f32_16x16x32_bf16 v[42:45], v[186:189], v[194:197], v[42:45]
	v_mfma_f32_16x16x32_bf16 v[34:37], v[174:177], v[202:205], v[34:37]
	v_mfma_f32_16x16x32_bf16 v[26:29], v[186:189], v[202:205], v[26:29]
	v_mfma_f32_16x16x32_bf16 v[18:21], v[174:177], v[210:213], v[18:21]
	v_mfma_f32_16x16x32_bf16 v[10:13], v[186:189], v[210:213], v[10:13]
	v_mfma_f32_16x16x32_bf16 v[6:9], v[174:177], v[218:221], v[6:9]
	v_mfma_f32_16x16x32_bf16 v[2:5], v[186:189], v[218:221], v[2:5]
	s_setprio 0
	s_add_i32 s74, s74, 2
	s_add_u32 s72, s72, 0x100
	s_addc_u32 s73, s73, 0
	s_add_u32 s38, s38, 0x100
	s_addc_u32 s39, s39, 0
	s_cmp_gt_u32 s74, 13
	s_barrier
	s_cbranch_scc0 .LBB0_647
	v_lshl_add_u32 v154, s36, 8, v1
	v_lshl_or_b32 v146, s67, 8, v149
	v_ashrrev_i32_e32 v155, 31, v154
	v_ashrrev_i32_e32 v147, 31, v146
	v_lshlrev_b64 v[156:157], 11, v[154:155]
	v_lshl_add_u64 v[156:157], s[6:7], 0, v[156:157]
	v_lshlrev_b64 v[158:159], 1, v[146:147]
	v_lshl_add_u64 v[146:147], v[156:157], 0, v[158:159]
	v_cvt_pk_bf16_f32 v126, v126, v127
	v_cvt_pk_bf16_f32 v127, v128, v129
	v_cvt_pk_bf16_f32 v128, v122, v123
	v_cvt_pk_bf16_f32 v129, v124, v125
	global_store_dwordx4 v[146:147], v[126:129], off
	v_cvt_pk_bf16_f32 v114, v114, v115
	v_cvt_pk_bf16_f32 v115, v116, v117
	v_cvt_pk_bf16_f32 v116, v106, v107
	v_or_b32_e32 v106, 16, v154
	v_ashrrev_i32_e32 v107, 31, v106
	v_lshlrev_b64 v[106:107], 11, v[106:107]
	v_lshl_add_u64 v[106:107], s[6:7], 0, v[106:107]
	v_cvt_pk_bf16_f32 v117, v108, v109
	global_store_dwordx4 v[146:147], v[114:117], off offset:256
	s_mov_b32 s67, s24
	s_mov_b32 s36, s26
	v_lshl_add_u64 v[114:115], v[106:107], 0, v[158:159]
	v_cvt_pk_bf16_f32 v106, v118, v119
	v_cvt_pk_bf16_f32 v107, v120, v121
	v_cvt_pk_bf16_f32 v108, v110, v111
	v_cvt_pk_bf16_f32 v109, v112, v113
	global_store_dwordx4 v[114:115], v[106:109], off
	v_cvt_pk_bf16_f32 v98, v98, v99
	v_cvt_pk_bf16_f32 v99, v100, v101
	v_cvt_pk_bf16_f32 v100, v90, v91
	v_or_b32_e32 v90, 32, v154
	v_ashrrev_i32_e32 v91, 31, v90
	v_lshlrev_b64 v[90:91], 11, v[90:91]
	v_lshl_add_u64 v[90:91], s[6:7], 0, v[90:91]
	v_cvt_pk_bf16_f32 v101, v92, v93
	global_store_dwordx4 v[114:115], v[98:101], off offset:256
	s_mov_b64 s[38:39], s[30:31]
	s_mov_b64 s[40:41], s[28:29]
	v_lshl_add_u64 v[98:99], v[90:91], 0, v[158:159]
	v_cvt_pk_bf16_f32 v90, v102, v103
	v_cvt_pk_bf16_f32 v91, v104, v105
	v_cvt_pk_bf16_f32 v92, v94, v95
	v_cvt_pk_bf16_f32 v93, v96, v97
	global_store_dwordx4 v[98:99], v[90:93], off
	v_cvt_pk_bf16_f32 v82, v82, v83
	v_cvt_pk_bf16_f32 v83, v84, v85
	v_cvt_pk_bf16_f32 v84, v74, v75
	v_or_b32_e32 v74, 48, v154
	v_ashrrev_i32_e32 v75, 31, v74
	v_lshlrev_b64 v[74:75], 11, v[74:75]
	v_lshl_add_u64 v[74:75], s[6:7], 0, v[74:75]
	v_cvt_pk_bf16_f32 v85, v76, v77
	global_store_dwordx4 v[98:99], v[82:85], off offset:256
	s_nop 1
	v_lshl_add_u64 v[82:83], v[74:75], 0, v[158:159]
	v_cvt_pk_bf16_f32 v74, v86, v87
	v_cvt_pk_bf16_f32 v75, v88, v89
	v_cvt_pk_bf16_f32 v76, v78, v79
	v_cvt_pk_bf16_f32 v77, v80, v81
	global_store_dwordx4 v[82:83], v[74:77], off
	v_cvt_pk_bf16_f32 v70, v70, v71
	v_cvt_pk_bf16_f32 v71, v72, v73
	v_cvt_pk_bf16_f32 v72, v66, v67
	v_cvt_pk_bf16_f32 v73, v68, v69
	global_store_dwordx4 v[82:83], v[70:73], off offset:256
	v_cvt_pk_bf16_f32 v62, v62, v63
	v_cvt_pk_bf16_f32 v63, v64, v65
	v_cvt_pk_bf16_f32 v64, v58, v59
	v_add_co_u32_e32 v58, vcc, s62, v146
	v_lshl_add_u64 v[66:67], v[146:147], 0, s[12:13]
	s_nop 0
	v_addc_co_u32_e32 v59, vcc, 0, v147, vcc
	v_cvt_pk_bf16_f32 v65, v60, v61
	global_store_dwordx4 v[58:59], v[62:65], off
	v_cvt_pk_bf16_f32 v50, v50, v51
	v_cvt_pk_bf16_f32 v51, v52, v53
	v_cvt_pk_bf16_f32 v52, v42, v43
	v_cvt_pk_bf16_f32 v53, v44, v45
	global_store_dwordx4 v[66:67], v[50:53], off offset:256
	v_cvt_pk_bf16_f32 v42, v54, v55
	v_cvt_pk_bf16_f32 v43, v56, v57
	v_cvt_pk_bf16_f32 v44, v46, v47
	v_add_co_u32_e32 v46, vcc, s63, v146
	s_nop 0
	v_lshl_add_u64 v[50:51], v[146:147], 0, s[16:17]
	v_addc_co_u32_e32 v47, vcc, 0, v147, vcc
	v_cvt_pk_bf16_f32 v45, v48, v49
	global_store_dwordx4 v[46:47], v[42:45], off
	v_cvt_pk_bf16_f32 v34, v34, v35
	v_cvt_pk_bf16_f32 v35, v36, v37
	v_cvt_pk_bf16_f32 v36, v26, v27
	v_cvt_pk_bf16_f32 v37, v28, v29
	global_store_dwordx4 v[50:51], v[34:37], off offset:256
	v_cvt_pk_bf16_f32 v26, v38, v39
	v_cvt_pk_bf16_f32 v27, v40, v41
	v_cvt_pk_bf16_f32 v28, v30, v31
	v_add_co_u32_e32 v30, vcc, s64, v146
	s_nop 0
	v_lshl_add_u64 v[34:35], v[146:147], 0, s[18:19]
	v_addc_co_u32_e32 v31, vcc, 0, v147, vcc
	v_cvt_pk_bf16_f32 v29, v32, v33
	global_store_dwordx4 v[30:31], v[26:29], off
	v_cvt_pk_bf16_f32 v18, v18, v19
	v_cvt_pk_bf16_f32 v19, v20, v21
	v_cvt_pk_bf16_f32 v20, v10, v11
	v_cvt_pk_bf16_f32 v21, v12, v13
	global_store_dwordx4 v[34:35], v[18:21], off offset:256
	v_cvt_pk_bf16_f32 v10, v22, v23
	v_cvt_pk_bf16_f32 v11, v24, v25
	v_cvt_pk_bf16_f32 v12, v14, v15
	v_add_co_u32_e32 v14, vcc, s66, v146
	s_nop 0
	v_lshl_add_u64 v[18:19], v[146:147], 0, s[20:21]
	v_addc_co_u32_e32 v15, vcc, 0, v147, vcc
	s_and_b64 vcc, exec, s[4:5]
	v_cvt_pk_bf16_f32 v13, v16, v17
	global_store_dwordx4 v[14:15], v[10:13], off
	v_cvt_pk_bf16_f32 v6, v6, v7
	v_cvt_pk_bf16_f32 v7, v8, v9
	v_cvt_pk_bf16_f32 v8, v2, v3
	v_cvt_pk_bf16_f32 v9, v4, v5
	global_store_dwordx4 v[18:19], v[6:9], off offset:256
	s_cbranch_vccz .LBB0_640
	s_waitcnt vmcnt(0)
	s_cmpk_gt_u32 s44, 0xff
	s_cbranch_scc1 .LBB0_651
	s_barrier

.LBB0_814:
	ds_read_b128 v[148:151], v155
	ds_read_b128 v[158:161], v155 offset:1024
	ds_read_b128 v[162:165], v155 offset:2048
	ds_read_b128 v[166:169], v155 offset:3072
	ds_read_b128 v[170:173], v156
	ds_read_b128 v[174:177], v156 offset:1024
	ds_read_b128 v[178:181], v156 offset:2048
	ds_read_b128 v[186:189], v156 offset:3072
	s_add_u32 s42, s40, 0xfffc0080
	s_addc_u32 s43, s41, -1
	s_cmp_eq_u32 s73, 12
	s_cselect_b32 s45, s7, s43
	s_cselect_b32 s44, s29, s42
	s_cselect_b32 s43, s27, s72
	s_cselect_b32 s42, s68, s69
	v_lshl_add_u64 v[152:153], s[40:41], 0, v[140:141]
	s_add_i32 m0, s39, 0xc000
	ds_read_b128 v[190:193], v157
	ds_read_b128 v[194:197], v157 offset:1024
	ds_read_b128 v[198:201], v157 offset:2048
	ds_read_b128 v[202:205], v157 offset:3072
	ds_read_b128 v[206:209], v157 offset:4096
	ds_read_b128 v[210:213], v157 offset:5120
	ds_read_b128 v[214:217], v157 offset:6144
	ds_read_b128 v[218:221], v157 offset:7168
	global_load_lds_dwordx4 v[152:153], off
	v_lshl_add_u64 v[152:153], s[40:41], 0, v[142:143]
	s_add_i32 m0, s39, 0xe000
	s_nop 0
	global_load_lds_dwordx4 v[152:153], off
	s_waitcnt vmcnt(8)
	s_waitcnt lgkmcnt(0)
	s_barrier
	s_setprio 1
	s_waitcnt lgkmcnt(0)
	v_mfma_f32_16x16x32_bf16 v[126:129], v[148:151], v[190:193], v[126:129]
	v_mfma_f32_16x16x32_bf16 v[122:125], v[162:165], v[190:193], v[122:125]
	v_mfma_f32_16x16x32_bf16 v[110:113], v[148:151], v[198:201], v[110:113]
	v_mfma_f32_16x16x32_bf16 v[106:109], v[162:165], v[198:201], v[106:109]
	v_mfma_f32_16x16x32_bf16 v[94:97], v[148:151], v[206:209], v[94:97]
	v_mfma_f32_16x16x32_bf16 v[90:93], v[162:165], v[206:209], v[90:93]
	v_mfma_f32_16x16x32_bf16 v[78:81], v[148:151], v[214:217], v[78:81]
	v_mfma_f32_16x16x32_bf16 v[74:77], v[162:165], v[214:217], v[74:77]
	v_mfma_f32_16x16x32_bf16 v[126:129], v[158:161], v[194:197], v[126:129]
	v_mfma_f32_16x16x32_bf16 v[122:125], v[166:169], v[194:197], v[122:125]
	v_mfma_f32_16x16x32_bf16 v[110:113], v[158:161], v[202:205], v[110:113]
	v_mfma_f32_16x16x32_bf16 v[106:109], v[166:169], v[202:205], v[106:109]
	v_mfma_f32_16x16x32_bf16 v[94:97], v[158:161], v[210:213], v[94:97]
	v_mfma_f32_16x16x32_bf16 v[90:93], v[166:169], v[210:213], v[90:93]
	v_mfma_f32_16x16x32_bf16 v[78:81], v[158:161], v[218:221], v[78:81]
	v_mfma_f32_16x16x32_bf16 v[74:77], v[166:169], v[218:221], v[74:77]
	s_setprio 0
	s_setprio 1
	v_mfma_f32_16x16x32_bf16 v[118:121], v[170:173], v[190:193], v[118:121]
	v_mfma_f32_16x16x32_bf16 v[114:117], v[178:181], v[190:193], v[114:117]
	v_mfma_f32_16x16x32_bf16 v[102:105], v[170:173], v[198:201], v[102:105]
	v_mfma_f32_16x16x32_bf16 v[98:101], v[178:181], v[198:201], v[98:101]
	v_mfma_f32_16x16x32_bf16 v[86:89], v[170:173], v[206:209], v[86:89]
	v_mfma_f32_16x16x32_bf16 v[82:85], v[178:181], v[206:209], v[82:85]
	v_mfma_f32_16x16x32_bf16 v[70:73], v[170:173], v[214:217], v[70:73]
	v_mfma_f32_16x16x32_bf16 v[66:69], v[178:181], v[214:217], v[66:69]
	v_mfma_f32_16x16x32_bf16 v[118:121], v[174:177], v[194:197], v[118:121]
	v_mfma_f32_16x16x32_bf16 v[114:117], v[186:189], v[194:197], v[114:117]
	v_mfma_f32_16x16x32_bf16 v[102:105], v[174:177], v[202:205], v[102:105]
	v_mfma_f32_16x16x32_bf16 v[98:101], v[186:189], v[202:205], v[98:101]
	v_mfma_f32_16x16x32_bf16 v[86:89], v[174:177], v[210:213], v[86:89]
	v_mfma_f32_16x16x32_bf16 v[82:85], v[186:189], v[210:213], v[82:85]
	v_mfma_f32_16x16x32_bf16 v[70:73], v[174:177], v[218:221], v[70:73]
	v_mfma_f32_16x16x32_bf16 v[66:69], v[186:189], v[218:221], v[66:69]
	s_setprio 0
	s_barrier
	s_add_i32 s54, s63, s47
	v_lshl_add_u64 v[152:153], s[42:43], 0, v[132:133]
	s_mov_b32 m0, s54
	ds_read_b128 v[190:193], v157 offset:16384
	ds_read_b128 v[194:197], v157 offset:17408
	ds_read_b128 v[198:201], v157 offset:18432
	ds_read_b128 v[202:205], v157 offset:19456
	ds_read_b128 v[206:209], v157 offset:20480
	ds_read_b128 v[210:213], v157 offset:21504
	ds_read_b128 v[214:217], v157 offset:22528
	ds_read_b128 v[218:221], v157 offset:23552
	global_load_lds_dwordx4 v[152:153], off
	s_add_i32 m0, s54, 0x2000
	s_add_u32 s54, s42, 0x40000
	v_lshl_add_u64 v[182:183], s[42:43], 0, v[136:137]
	s_addc_u32 s55, s43, 0
	s_add_i32 s56, s64, s47
	global_load_lds_dwordx4 v[182:183], off
	v_lshl_add_u64 v[222:223], s[54:55], 0, v[132:133]
	s_mov_b32 m0, s56
	v_lshl_add_u64 v[224:225], s[44:45], 0, v[134:135]
	global_load_lds_dwordx4 v[222:223], off
	v_lshl_add_u64 v[222:223], s[54:55], 0, v[136:137]
	s_add_i32 m0, s56, 0x2000
	s_nop 0
	global_load_lds_dwordx4 v[222:223], off
	v_lshl_add_u64 v[222:223], s[44:45], 0, v[130:131]
	s_mov_b32 m0, s39
	s_nop 0
	global_load_lds_dwordx4 v[222:223], off
	s_mov_b32 m0, s48
	s_nop 0
	global_load_lds_dwordx4 v[224:225], off
	s_waitcnt vmcnt(8)
	s_waitcnt lgkmcnt(0)
	s_barrier
	s_setprio 1
	s_waitcnt lgkmcnt(0)
	v_mfma_f32_16x16x32_bf16 v[62:65], v[148:151], v[190:193], v[62:65]
	v_mfma_f32_16x16x32_bf16 v[58:61], v[162:165], v[190:193], v[58:61]
	v_mfma_f32_16x16x32_bf16 v[46:49], v[148:151], v[198:201], v[46:49]
	v_mfma_f32_16x16x32_bf16 v[42:45], v[162:165], v[198:201], v[42:45]
	v_mfma_f32_16x16x32_bf16 v[30:33], v[148:151], v[206:209], v[30:33]
	v_mfma_f32_16x16x32_bf16 v[26:29], v[162:165], v[206:209], v[26:29]
	v_mfma_f32_16x16x32_bf16 v[14:17], v[148:151], v[214:217], v[14:17]
	v_mfma_f32_16x16x32_bf16 v[10:13], v[162:165], v[214:217], v[10:13]
	v_mfma_f32_16x16x32_bf16 v[62:65], v[158:161], v[194:197], v[62:65]
	v_mfma_f32_16x16x32_bf16 v[58:61], v[166:169], v[194:197], v[58:61]
	v_mfma_f32_16x16x32_bf16 v[46:49], v[158:161], v[202:205], v[46:49]
	v_mfma_f32_16x16x32_bf16 v[42:45], v[166:169], v[202:205], v[42:45]
	v_mfma_f32_16x16x32_bf16 v[30:33], v[158:161], v[210:213], v[30:33]
	v_mfma_f32_16x16x32_bf16 v[26:29], v[166:169], v[210:213], v[26:29]
	v_mfma_f32_16x16x32_bf16 v[14:17], v[158:161], v[218:221], v[14:17]
	v_mfma_f32_16x16x32_bf16 v[10:13], v[166:169], v[218:221], v[10:13]
	s_setprio 0
	s_setprio 1
	v_mfma_f32_16x16x32_bf16 v[54:57], v[170:173], v[190:193], v[54:57]
	v_mfma_f32_16x16x32_bf16 v[50:53], v[178:181], v[190:193], v[50:53]
	v_mfma_f32_16x16x32_bf16 v[38:41], v[170:173], v[198:201], v[38:41]
	v_mfma_f32_16x16x32_bf16 v[34:37], v[178:181], v[198:201], v[34:37]
	v_mfma_f32_16x16x32_bf16 v[22:25], v[170:173], v[206:209], v[22:25]
	v_mfma_f32_16x16x32_bf16 v[18:21], v[178:181], v[206:209], v[18:21]
	v_mfma_f32_16x16x32_bf16 v[6:9], v[170:173], v[214:217], v[6:9]
	v_mfma_f32_16x16x32_bf16 v[2:5], v[178:181], v[214:217], v[2:5]
	v_mfma_f32_16x16x32_bf16 v[54:57], v[174:177], v[194:197], v[54:57]
	v_mfma_f32_16x16x32_bf16 v[50:53], v[186:189], v[194:197], v[50:53]
	v_mfma_f32_16x16x32_bf16 v[38:41], v[174:177], v[202:205], v[38:41]
	v_mfma_f32_16x16x32_bf16 v[34:37], v[186:189], v[202:205], v[34:37]
	v_mfma_f32_16x16x32_bf16 v[22:25], v[174:177], v[210:213], v[22:25]
	v_mfma_f32_16x16x32_bf16 v[18:21], v[186:189], v[210:213], v[18:21]
	v_mfma_f32_16x16x32_bf16 v[6:9], v[174:177], v[218:221], v[6:9]
	v_mfma_f32_16x16x32_bf16 v[2:5], v[186:189], v[218:221], v[2:5]
	s_setprio 0
	s_barrier
	s_add_i32 s54, 0, 0x18000
	s_add_i32 s55, 0, 0x1c000
	v_add_u32_e32 v166, s54, v154
	v_add_u32_e32 v185, s55, v154
	ds_read_b128 v[148:151], v166
	ds_read_b128 v[158:161], v166 offset:1024
	ds_read_b128 v[162:165], v166 offset:2048
	ds_read_b128 v[166:169], v166 offset:3072
	ds_read_b128 v[170:173], v185
	ds_read_b128 v[174:177], v185 offset:1024
	ds_read_b128 v[178:181], v185 offset:2048
	ds_read_b128 v[186:189], v185 offset:3072
	s_add_u32 s44, s44, 0x40000
	s_addc_u32 s45, s45, 0
	s_mov_b32 m0, s49
	v_lshl_add_u64 v[226:227], s[44:45], 0, v[130:131]
	ds_read_b128 v[190:193], v157 offset:32768
	ds_read_b128 v[194:197], v157 offset:33792
	ds_read_b128 v[198:201], v157 offset:34816
	ds_read_b128 v[202:205], v157 offset:35840
	ds_read_b128 v[206:209], v157 offset:36864
	ds_read_b128 v[210:213], v157 offset:37888
	ds_read_b128 v[214:217], v157 offset:38912
	ds_read_b128 v[218:221], v157 offset:39936
	global_load_lds_dwordx4 v[226:227], off
	v_lshl_add_u64 v[226:227], s[44:45], 0, v[134:135]
	s_mov_b32 m0, s50
	s_nop 0
	global_load_lds_dwordx4 v[226:227], off
	s_waitcnt vmcnt(8)
	s_waitcnt lgkmcnt(0)
	s_barrier
	s_setprio 1
	s_waitcnt lgkmcnt(0)
	v_mfma_f32_16x16x32_bf16 v[126:129], v[148:151], v[190:193], v[126:129]
	v_mfma_f32_16x16x32_bf16 v[122:125], v[162:165], v[190:193], v[122:125]
	v_mfma_f32_16x16x32_bf16 v[110:113], v[148:151], v[198:201], v[110:113]
	v_mfma_f32_16x16x32_bf16 v[106:109], v[162:165], v[198:201], v[106:109]
	v_mfma_f32_16x16x32_bf16 v[94:97], v[148:151], v[206:209], v[94:97]
	v_mfma_f32_16x16x32_bf16 v[90:93], v[162:165], v[206:209], v[90:93]
	v_mfma_f32_16x16x32_bf16 v[78:81], v[148:151], v[214:217], v[78:81]
	v_mfma_f32_16x16x32_bf16 v[74:77], v[162:165], v[214:217], v[74:77]
	v_mfma_f32_16x16x32_bf16 v[126:129], v[158:161], v[194:197], v[126:129]
	v_mfma_f32_16x16x32_bf16 v[122:125], v[166:169], v[194:197], v[122:125]
	v_mfma_f32_16x16x32_bf16 v[110:113], v[158:161], v[202:205], v[110:113]
	v_mfma_f32_16x16x32_bf16 v[106:109], v[166:169], v[202:205], v[106:109]
	v_mfma_f32_16x16x32_bf16 v[94:97], v[158:161], v[210:213], v[94:97]
	v_mfma_f32_16x16x32_bf16 v[90:93], v[166:169], v[210:213], v[90:93]
	v_mfma_f32_16x16x32_bf16 v[78:81], v[158:161], v[218:221], v[78:81]
	v_mfma_f32_16x16x32_bf16 v[74:77], v[166:169], v[218:221], v[74:77]
	s_setprio 0
	s_setprio 1
	v_mfma_f32_16x16x32_bf16 v[118:121], v[170:173], v[190:193], v[118:121]
	v_mfma_f32_16x16x32_bf16 v[114:117], v[178:181], v[190:193], v[114:117]
	v_mfma_f32_16x16x32_bf16 v[102:105], v[170:173], v[198:201], v[102:105]
	v_mfma_f32_16x16x32_bf16 v[98:101], v[178:181], v[198:201], v[98:101]
	v_mfma_f32_16x16x32_bf16 v[86:89], v[170:173], v[206:209], v[86:89]
	v_mfma_f32_16x16x32_bf16 v[82:85], v[178:181], v[206:209], v[82:85]
	v_mfma_f32_16x16x32_bf16 v[70:73], v[170:173], v[214:217], v[70:73]
	v_mfma_f32_16x16x32_bf16 v[66:69], v[178:181], v[214:217], v[66:69]
	v_mfma_f32_16x16x32_bf16 v[118:121], v[174:177], v[194:197], v[118:121]
	v_mfma_f32_16x16x32_bf16 v[114:117], v[186:189], v[194:197], v[114:117]
	v_mfma_f32_16x16x32_bf16 v[102:105], v[174:177], v[202:205], v[102:105]
	v_mfma_f32_16x16x32_bf16 v[98:101], v[186:189], v[202:205], v[98:101]
	v_mfma_f32_16x16x32_bf16 v[86:89], v[174:177], v[210:213], v[86:89]
	v_mfma_f32_16x16x32_bf16 v[82:85], v[186:189], v[210:213], v[82:85]
	v_mfma_f32_16x16x32_bf16 v[70:73], v[174:177], v[218:221], v[70:73]
	v_mfma_f32_16x16x32_bf16 v[66:69], v[186:189], v[218:221], v[66:69]
	s_setprio 0
	s_barrier
	s_add_i32 s44, s54, s47
	v_lshl_add_u64 v[152:153], v[152:153], 0, s[14:15]
	s_mov_b32 m0, s44
	ds_read_b128 v[190:193], v157 offset:49152
	ds_read_b128 v[194:197], v157 offset:50176
	ds_read_b128 v[198:201], v157 offset:51200
	ds_read_b128 v[202:205], v157 offset:52224
	ds_read_b128 v[206:209], v157 offset:53248
	ds_read_b128 v[210:213], v157 offset:54272
	ds_read_b128 v[214:217], v157 offset:55296
	ds_read_b128 v[218:221], v157 offset:56320
	global_load_lds_dwordx4 v[152:153], off
	s_add_i32 m0, s44, 0x2000
	s_add_u32 s42, s42, 0x40080
	v_lshl_add_u64 v[152:153], v[182:183], 0, s[14:15]
	s_addc_u32 s43, s43, 0
	s_add_i32 s44, s55, s47
	global_load_lds_dwordx4 v[152:153], off
	v_lshl_add_u64 v[152:153], s[42:43], 0, v[132:133]
	s_mov_b32 m0, s44
	s_nop 0
	global_load_lds_dwordx4 v[152:153], off
	v_lshl_add_u64 v[152:153], s[42:43], 0, v[136:137]
	s_add_i32 m0, s44, 0x2000
	s_nop 0
	global_load_lds_dwordx4 v[152:153], off
	v_lshl_add_u64 v[152:153], v[222:223], 0, s[14:15]
	s_mov_b32 m0, s60
	s_nop 0
	global_load_lds_dwordx4 v[152:153], off
	v_lshl_add_u64 v[152:153], v[224:225], 0, s[14:15]
	s_mov_b32 m0, s61
	s_nop 0
	global_load_lds_dwordx4 v[152:153], off
	s_waitcnt vmcnt(8)
	s_waitcnt lgkmcnt(0)
	s_barrier
	s_setprio 1
	s_waitcnt lgkmcnt(0)
	v_mfma_f32_16x16x32_bf16 v[62:65], v[148:151], v[190:193], v[62:65]
	v_mfma_f32_16x16x32_bf16 v[58:61], v[162:165], v[190:193], v[58:61]
	v_mfma_f32_16x16x32_bf16 v[46:49], v[148:151], v[198:201], v[46:49]
	v_mfma_f32_16x16x32_bf16 v[42:45], v[162:165], v[198:201], v[42:45]
	v_mfma_f32_16x16x32_bf16 v[30:33], v[148:151], v[206:209], v[30:33]
	v_mfma_f32_16x16x32_bf16 v[26:29], v[162:165], v[206:209], v[26:29]
	v_mfma_f32_16x16x32_bf16 v[14:17], v[148:151], v[214:217], v[14:17]
	v_mfma_f32_16x16x32_bf16 v[10:13], v[162:165], v[214:217], v[10:13]
	v_mfma_f32_16x16x32_bf16 v[62:65], v[158:161], v[194:197], v[62:65]
	v_mfma_f32_16x16x32_bf16 v[58:61], v[166:169], v[194:197], v[58:61]
	v_mfma_f32_16x16x32_bf16 v[46:49], v[158:161], v[202:205], v[46:49]
	v_mfma_f32_16x16x32_bf16 v[42:45], v[166:169], v[202:205], v[42:45]
	v_mfma_f32_16x16x32_bf16 v[30:33], v[158:161], v[210:213], v[30:33]
	v_mfma_f32_16x16x32_bf16 v[26:29], v[166:169], v[210:213], v[26:29]
	v_mfma_f32_16x16x32_bf16 v[14:17], v[158:161], v[218:221], v[14:17]
	v_mfma_f32_16x16x32_bf16 v[10:13], v[166:169], v[218:221], v[10:13]
	s_setprio 0
	s_setprio 1
	v_mfma_f32_16x16x32_bf16 v[54:57], v[170:173], v[190:193], v[54:57]
	v_mfma_f32_16x16x32_bf16 v[50:53], v[178:181], v[190:193], v[50:53]
	v_mfma_f32_16x16x32_bf16 v[38:41], v[170:173], v[198:201], v[38:41]
	v_mfma_f32_16x16x32_bf16 v[34:37], v[178:181], v[198:201], v[34:37]
	v_mfma_f32_16x16x32_bf16 v[22:25], v[170:173], v[206:209], v[22:25]
	v_mfma_f32_16x16x32_bf16 v[18:21], v[178:181], v[206:209], v[18:21]
	v_mfma_f32_16x16x32_bf16 v[6:9], v[170:173], v[214:217], v[6:9]
	v_mfma_f32_16x16x32_bf16 v[2:5], v[178:181], v[214:217], v[2:5]
	v_mfma_f32_16x16x32_bf16 v[54:57], v[174:177], v[194:197], v[54:57]
	v_mfma_f32_16x16x32_bf16 v[50:53], v[186:189], v[194:197], v[50:53]
	v_mfma_f32_16x16x32_bf16 v[38:41], v[174:177], v[202:205], v[38:41]
	v_mfma_f32_16x16x32_bf16 v[34:37], v[186:189], v[202:205], v[34:37]
	v_mfma_f32_16x16x32_bf16 v[22:25], v[174:177], v[210:213], v[22:25]
	v_mfma_f32_16x16x32_bf16 v[18:21], v[186:189], v[210:213], v[18:21]
	v_mfma_f32_16x16x32_bf16 v[6:9], v[174:177], v[218:221], v[6:9]
	v_mfma_f32_16x16x32_bf16 v[2:5], v[186:189], v[218:221], v[2:5]
	s_setprio 0
	s_add_i32 s73, s73, 2
	s_add_u32 s40, s40, 0x100
	s_addc_u32 s41, s41, 0
	s_add_u32 s69, s69, 0x100
	s_addc_u32 s72, s72, 0
	s_cmp_gt_u32 s73, 13
	s_barrier
	s_cbranch_scc0 .LBB0_814
	s_cmp_gt_i32 s6, 3
	s_cselect_b64 s[40:41], -1, 0
	s_cmp_lt_i32 s6, 4
	s_cbranch_scc1 .LBB0_817
	v_mul_f32_e32 v148, 0xbfb8aa3b, v126
	v_mul_f32_e32 v149, 0xbfb8aa3b, v127
	v_mul_f32_e32 v150, 0xbfb8aa3b, v128
	v_mul_f32_e32 v151, 0xbfb8aa3b, v129
	v_mul_f32_e32 v152, 0xbfb8aa3b, v122
	v_mul_f32_e32 v153, 0xbfb8aa3b, v123
	v_mul_f32_e32 v158, 0xbfb8aa3b, v124
	v_mul_f32_e32 v159, 0xbfb8aa3b, v125
	v_exp_f32_e32 v148, v148
	v_exp_f32_e32 v149, v149
	v_exp_f32_e32 v150, v150
	v_exp_f32_e32 v151, v151
	v_exp_f32_e32 v152, v152
	v_exp_f32_e32 v153, v153
	v_exp_f32_e32 v158, v158
	v_exp_f32_e32 v159, v159
	v_add_f32_e32 v148, 1.0, v148
	v_add_f32_e32 v149, 1.0, v149
	v_add_f32_e32 v150, 1.0, v150
	v_add_f32_e32 v151, 1.0, v151
	v_add_f32_e32 v152, 1.0, v152
	v_add_f32_e32 v153, 1.0, v153
	v_add_f32_e32 v158, 1.0, v158
	v_add_f32_e32 v159, 1.0, v159
	v_rcp_f32_e32 v148, v148
	v_rcp_f32_e32 v149, v149
	v_rcp_f32_e32 v150, v150
	v_rcp_f32_e32 v151, v151
	v_rcp_f32_e32 v152, v152
	v_rcp_f32_e32 v158, v158
	v_rcp_f32_e32 v159, v159
	v_rcp_f32_e32 v153, v153
	v_pk_mul_f32 v[128:129], v[128:129], v[150:151]
	v_pk_mul_f32 v[126:127], v[126:127], v[148:149]
	v_pk_mul_f32 v[124:125], v[124:125], v[158:159]
	v_pk_mul_f32 v[122:123], v[122:123], v[152:153]

.LBB0_1008:
	s_or_b32 s46, s77, 1
	v_add_u32_e32 v140, s66, v143
	s_mul_hi_u32 s55, s46, 0x420000
	s_mul_i32 s54, s46, 0x420000
	s_lshl_b32 s46, s77, 7
	ds_read_b128 v[146:149], v140
	ds_read_b128 v[150:153], v140 offset:1024
	ds_read_b128 v[154:157], v140 offset:2048
	ds_read_b128 v[158:161], v140 offset:3072
	v_add_u32_e32 v140, s67, v143
	s_add_u32 s46, s38, s46
	ds_read_b128 v[162:165], v140
	ds_read_b128 v[166:169], v140 offset:1024
	ds_read_b128 v[170:173], v140 offset:2048
	ds_read_b128 v[174:177], v140 offset:3072
	s_addc_u32 s47, s39, 0
	s_add_u32 s56, s46, 0x100
	s_addc_u32 s57, s47, 0
	s_add_u32 s46, s44, 0x420000
	s_addc_u32 s47, s45, 0
	s_and_b64 s[48:49], exec, s[48:49]
	s_cselect_b32 s49, s25, s57
	s_cselect_b32 s48, s27, s56
	s_add_u32 s54, s75, s54
	s_addc_u32 s55, s76, s55
	v_lshl_add_u64 v[140:141], s[54:55], 0, v[128:129]
	s_add_i32 m0, s37, 0xc000
	ds_read_b128 v[178:181], v145
	ds_read_b128 v[186:189], v145 offset:1024
	ds_read_b128 v[190:193], v145 offset:2048
	ds_read_b128 v[194:197], v145 offset:3072
	ds_read_b128 v[198:201], v145 offset:4096
	ds_read_b128 v[202:205], v145 offset:5120
	ds_read_b128 v[206:209], v145 offset:6144
	ds_read_b128 v[210:213], v145 offset:7168
	global_load_lds_dwordx4 v[140:141], off
	v_lshl_add_u64 v[140:141], s[54:55], 0, v[132:133]
	s_add_i32 m0, s37, 0xe000
	s_nop 0
	global_load_lds_dwordx4 v[140:141], off
	s_waitcnt vmcnt(8)
	s_waitcnt lgkmcnt(0)
	s_barrier
	s_setprio 1
	s_waitcnt lgkmcnt(0)
	v_mfma_f32_16x16x32_bf16 v[124:127], v[146:149], v[178:181], v[124:127]
	v_mfma_f32_16x16x32_bf16 v[120:123], v[154:157], v[178:181], v[120:123]
	v_mfma_f32_16x16x32_bf16 v[116:119], v[146:149], v[190:193], v[116:119]
	v_mfma_f32_16x16x32_bf16 v[108:111], v[154:157], v[190:193], v[108:111]
	v_mfma_f32_16x16x32_bf16 v[100:103], v[146:149], v[198:201], v[100:103]
	v_mfma_f32_16x16x32_bf16 v[92:95], v[154:157], v[198:201], v[92:95]
	v_mfma_f32_16x16x32_bf16 v[84:87], v[146:149], v[206:209], v[84:87]
	v_mfma_f32_16x16x32_bf16 v[76:79], v[154:157], v[206:209], v[76:79]
	v_mfma_f32_16x16x32_bf16 v[124:127], v[150:153], v[186:189], v[124:127]
	v_mfma_f32_16x16x32_bf16 v[120:123], v[158:161], v[186:189], v[120:123]
	v_mfma_f32_16x16x32_bf16 v[116:119], v[150:153], v[194:197], v[116:119]
	v_mfma_f32_16x16x32_bf16 v[108:111], v[158:161], v[194:197], v[108:111]
	v_mfma_f32_16x16x32_bf16 v[100:103], v[150:153], v[202:205], v[100:103]
	v_mfma_f32_16x16x32_bf16 v[92:95], v[158:161], v[202:205], v[92:95]
	v_mfma_f32_16x16x32_bf16 v[84:87], v[150:153], v[210:213], v[84:87]
	v_mfma_f32_16x16x32_bf16 v[76:79], v[158:161], v[210:213], v[76:79]
	s_setprio 0
	s_setprio 1
	v_mfma_f32_16x16x32_bf16 v[112:115], v[162:165], v[178:181], v[112:115]
	v_mfma_f32_16x16x32_bf16 v[104:107], v[170:173], v[178:181], v[104:107]
	v_mfma_f32_16x16x32_bf16 v[96:99], v[162:165], v[190:193], v[96:99]
	v_mfma_f32_16x16x32_bf16 v[88:91], v[170:173], v[190:193], v[88:91]
	v_mfma_f32_16x16x32_bf16 v[80:83], v[162:165], v[198:201], v[80:83]
	v_mfma_f32_16x16x32_bf16 v[72:75], v[170:173], v[198:201], v[72:75]
	v_mfma_f32_16x16x32_bf16 v[68:71], v[162:165], v[206:209], v[68:71]
	v_mfma_f32_16x16x32_bf16 v[64:67], v[170:173], v[206:209], v[64:67]
	v_mfma_f32_16x16x32_bf16 v[112:115], v[166:169], v[186:189], v[112:115]
	v_mfma_f32_16x16x32_bf16 v[104:107], v[174:177], v[186:189], v[104:107]
	v_mfma_f32_16x16x32_bf16 v[96:99], v[166:169], v[194:197], v[96:99]
	v_mfma_f32_16x16x32_bf16 v[88:91], v[174:177], v[194:197], v[88:91]
	v_mfma_f32_16x16x32_bf16 v[80:83], v[166:169], v[202:205], v[80:83]
	v_mfma_f32_16x16x32_bf16 v[72:75], v[174:177], v[202:205], v[72:75]
	v_mfma_f32_16x16x32_bf16 v[68:71], v[166:169], v[210:213], v[68:71]
	v_mfma_f32_16x16x32_bf16 v[64:67], v[174:177], v[210:213], v[64:67]
	s_setprio 0
	s_barrier
	s_add_i32 s54, s66, s50
	v_lshl_add_u64 v[140:141], s[48:49], 0, v[130:131]
	s_mov_b32 m0, s54
	ds_read_b128 v[178:181], v145 offset:16384
	ds_read_b128 v[186:189], v145 offset:17408
	ds_read_b128 v[190:193], v145 offset:18432
	ds_read_b128 v[194:197], v145 offset:19456
	ds_read_b128 v[198:201], v145 offset:20480
	ds_read_b128 v[202:205], v145 offset:21504
	ds_read_b128 v[206:209], v145 offset:22528
	ds_read_b128 v[210:213], v145 offset:23552
	global_load_lds_dwordx4 v[140:141], off
	s_add_i32 m0, s54, 0x2000
	s_add_u32 s54, s48, 0x40000
	v_lshl_add_u64 v[182:183], s[48:49], 0, v[134:135]
	s_addc_u32 s55, s49, 0
	s_add_i32 s56, s67, s50
	global_load_lds_dwordx4 v[182:183], off
	v_lshl_add_u64 v[214:215], s[54:55], 0, v[130:131]
	s_mov_b32 m0, s56
	s_nop 0
	global_load_lds_dwordx4 v[214:215], off
	v_lshl_add_u64 v[214:215], s[54:55], 0, v[134:135]
	s_add_i32 m0, s56, 0x2000
	s_nop 0
	global_load_lds_dwordx4 v[214:215], off
	v_lshl_add_u64 v[214:215], s[44:45], 0, v[128:129]
	s_mov_b32 m0, s37
	s_nop 0
	global_load_lds_dwordx4 v[214:215], off
	v_lshl_add_u64 v[214:215], s[44:45], 0, v[132:133]
	s_mov_b32 m0, s58
	s_nop 0
	global_load_lds_dwordx4 v[214:215], off
	s_waitcnt vmcnt(8)
	s_waitcnt lgkmcnt(0)
	s_barrier
	s_setprio 1
	s_waitcnt lgkmcnt(0)
	v_mfma_f32_16x16x32_bf16 v[60:63], v[146:149], v[178:181], v[60:63]
	v_mfma_f32_16x16x32_bf16 v[56:59], v[154:157], v[178:181], v[56:59]
	v_mfma_f32_16x16x32_bf16 v[52:55], v[146:149], v[190:193], v[52:55]
	v_mfma_f32_16x16x32_bf16 v[44:47], v[154:157], v[190:193], v[44:47]
	v_mfma_f32_16x16x32_bf16 v[36:39], v[146:149], v[198:201], v[36:39]
	v_mfma_f32_16x16x32_bf16 v[28:31], v[154:157], v[198:201], v[28:31]
	v_mfma_f32_16x16x32_bf16 v[20:23], v[146:149], v[206:209], v[20:23]
	v_mfma_f32_16x16x32_bf16 v[12:15], v[154:157], v[206:209], v[12:15]
	v_mfma_f32_16x16x32_bf16 v[60:63], v[150:153], v[186:189], v[60:63]
	v_mfma_f32_16x16x32_bf16 v[56:59], v[158:161], v[186:189], v[56:59]
	v_mfma_f32_16x16x32_bf16 v[52:55], v[150:153], v[194:197], v[52:55]
	v_mfma_f32_16x16x32_bf16 v[44:47], v[158:161], v[194:197], v[44:47]
	v_mfma_f32_16x16x32_bf16 v[36:39], v[150:153], v[202:205], v[36:39]
	v_mfma_f32_16x16x32_bf16 v[28:31], v[158:161], v[202:205], v[28:31]
	v_mfma_f32_16x16x32_bf16 v[20:23], v[150:153], v[210:213], v[20:23]
	v_mfma_f32_16x16x32_bf16 v[12:15], v[158:161], v[210:213], v[12:15]
	s_setprio 0
	s_setprio 1
	v_mfma_f32_16x16x32_bf16 v[48:51], v[162:165], v[178:181], v[48:51]
	v_mfma_f32_16x16x32_bf16 v[40:43], v[170:173], v[178:181], v[40:43]
	v_mfma_f32_16x16x32_bf16 v[32:35], v[162:165], v[190:193], v[32:35]
	v_mfma_f32_16x16x32_bf16 v[24:27], v[170:173], v[190:193], v[24:27]
	v_mfma_f32_16x16x32_bf16 v[16:19], v[162:165], v[198:201], v[16:19]
	v_mfma_f32_16x16x32_bf16 v[8:11], v[170:173], v[198:201], v[8:11]
	v_mfma_f32_16x16x32_bf16 v[4:7], v[162:165], v[206:209], v[4:7]
	v_mfma_f32_16x16x32_bf16 v[0:3], v[170:173], v[206:209], v[0:3]
	v_mfma_f32_16x16x32_bf16 v[48:51], v[166:169], v[186:189], v[48:51]
	v_mfma_f32_16x16x32_bf16 v[40:43], v[174:177], v[186:189], v[40:43]
	v_mfma_f32_16x16x32_bf16 v[32:35], v[166:169], v[194:197], v[32:35]
	v_mfma_f32_16x16x32_bf16 v[24:27], v[174:177], v[194:197], v[24:27]
	v_mfma_f32_16x16x32_bf16 v[16:19], v[166:169], v[202:205], v[16:19]
	v_mfma_f32_16x16x32_bf16 v[8:11], v[174:177], v[202:205], v[8:11]
	v_mfma_f32_16x16x32_bf16 v[4:7], v[166:169], v[210:213], v[4:7]
	v_mfma_f32_16x16x32_bf16 v[0:3], v[174:177], v[210:213], v[0:3]
	s_setprio 0
	s_barrier
	s_add_i32 s54, 0, 0x18000
	s_add_i32 s55, 0, 0x1c000
	v_add_u32_e32 v158, s54, v143
	v_add_u32_e32 v174, s55, v143
	ds_read_b128 v[146:149], v158
	ds_read_b128 v[150:153], v158 offset:1024
	ds_read_b128 v[154:157], v158 offset:2048
	ds_read_b128 v[158:161], v158 offset:3072
	ds_read_b128 v[162:165], v174
	ds_read_b128 v[166:169], v174 offset:1024
	ds_read_b128 v[170:173], v174 offset:2048
	ds_read_b128 v[174:177], v174 offset:3072
	s_add_u32 s44, s44, 0x4000
	s_addc_u32 s45, s45, 0
	s_mov_b32 m0, s59
	v_lshl_add_u64 v[214:215], s[44:45], 0, v[128:129]
	ds_read_b128 v[178:181], v145 offset:32768
	ds_read_b128 v[186:189], v145 offset:33792
	ds_read_b128 v[190:193], v145 offset:34816
	ds_read_b128 v[194:197], v145 offset:35840
	ds_read_b128 v[198:201], v145 offset:36864
	ds_read_b128 v[202:205], v145 offset:37888
	ds_read_b128 v[206:209], v145 offset:38912
	ds_read_b128 v[210:213], v145 offset:39936
	global_load_lds_dwordx4 v[214:215], off
	v_lshl_add_u64 v[214:215], s[44:45], 0, v[132:133]
	s_mov_b32 m0, s60
	s_nop 0
	global_load_lds_dwordx4 v[214:215], off
	s_waitcnt vmcnt(8)
	s_waitcnt lgkmcnt(0)
	s_barrier
	s_setprio 1
	s_waitcnt lgkmcnt(0)
	v_mfma_f32_16x16x32_bf16 v[124:127], v[146:149], v[178:181], v[124:127]
	v_mfma_f32_16x16x32_bf16 v[120:123], v[154:157], v[178:181], v[120:123]
	v_mfma_f32_16x16x32_bf16 v[116:119], v[146:149], v[190:193], v[116:119]
	v_mfma_f32_16x16x32_bf16 v[108:111], v[154:157], v[190:193], v[108:111]
	v_mfma_f32_16x16x32_bf16 v[100:103], v[146:149], v[198:201], v[100:103]
	v_mfma_f32_16x16x32_bf16 v[92:95], v[154:157], v[198:201], v[92:95]
	v_mfma_f32_16x16x32_bf16 v[84:87], v[146:149], v[206:209], v[84:87]
	v_mfma_f32_16x16x32_bf16 v[76:79], v[154:157], v[206:209], v[76:79]
	v_mfma_f32_16x16x32_bf16 v[124:127], v[150:153], v[186:189], v[124:127]
	v_mfma_f32_16x16x32_bf16 v[120:123], v[158:161], v[186:189], v[120:123]
	v_mfma_f32_16x16x32_bf16 v[116:119], v[150:153], v[194:197], v[116:119]
	v_mfma_f32_16x16x32_bf16 v[108:111], v[158:161], v[194:197], v[108:111]
	v_mfma_f32_16x16x32_bf16 v[100:103], v[150:153], v[202:205], v[100:103]
	v_mfma_f32_16x16x32_bf16 v[92:95], v[158:161], v[202:205], v[92:95]
	v_mfma_f32_16x16x32_bf16 v[84:87], v[150:153], v[210:213], v[84:87]
	v_mfma_f32_16x16x32_bf16 v[76:79], v[158:161], v[210:213], v[76:79]
	s_setprio 0
	s_setprio 1
	v_mfma_f32_16x16x32_bf16 v[112:115], v[162:165], v[178:181], v[112:115]
	v_mfma_f32_16x16x32_bf16 v[104:107], v[170:173], v[178:181], v[104:107]
	v_mfma_f32_16x16x32_bf16 v[96:99], v[162:165], v[190:193], v[96:99]
	v_mfma_f32_16x16x32_bf16 v[88:91], v[170:173], v[190:193], v[88:91]
	v_mfma_f32_16x16x32_bf16 v[80:83], v[162:165], v[198:201], v[80:83]
	v_mfma_f32_16x16x32_bf16 v[72:75], v[170:173], v[198:201], v[72:75]
	v_mfma_f32_16x16x32_bf16 v[68:71], v[162:165], v[206:209], v[68:71]
	v_mfma_f32_16x16x32_bf16 v[64:67], v[170:173], v[206:209], v[64:67]
	v_mfma_f32_16x16x32_bf16 v[112:115], v[166:169], v[186:189], v[112:115]
	v_mfma_f32_16x16x32_bf16 v[104:107], v[174:177], v[186:189], v[104:107]
	v_mfma_f32_16x16x32_bf16 v[96:99], v[166:169], v[194:197], v[96:99]
	v_mfma_f32_16x16x32_bf16 v[88:91], v[174:177], v[194:197], v[88:91]
	v_mfma_f32_16x16x32_bf16 v[80:83], v[166:169], v[202:205], v[80:83]
	v_mfma_f32_16x16x32_bf16 v[72:75], v[174:177], v[202:205], v[72:75]
	v_mfma_f32_16x16x32_bf16 v[68:71], v[166:169], v[210:213], v[68:71]
	v_mfma_f32_16x16x32_bf16 v[64:67], v[174:177], v[210:213], v[64:67]
	s_setprio 0
	s_barrier
	s_add_i32 s44, s54, s50
	v_lshl_add_u64 v[140:141], v[140:141], 0, s[14:15]
	s_mov_b32 m0, s44
	ds_read_b128 v[178:181], v145 offset:49152
	ds_read_b128 v[186:189], v145 offset:50176
	ds_read_b128 v[190:193], v145 offset:51200
	ds_read_b128 v[194:197], v145 offset:52224
	ds_read_b128 v[198:201], v145 offset:53248
	ds_read_b128 v[202:205], v145 offset:54272
	ds_read_b128 v[206:209], v145 offset:55296
	ds_read_b128 v[210:213], v145 offset:56320
	global_load_lds_dwordx4 v[140:141], off
	s_add_i32 m0, s44, 0x2000
	s_add_u32 s44, s48, 0x40080
	v_lshl_add_u64 v[140:141], v[182:183], 0, s[14:15]
	s_addc_u32 s45, s49, 0
	s_add_i32 s48, s55, s50
	global_load_lds_dwordx4 v[140:141], off
	v_lshl_add_u64 v[140:141], s[44:45], 0, v[130:131]
	s_mov_b32 m0, s48
	s_nop 0
	global_load_lds_dwordx4 v[140:141], off
	v_lshl_add_u64 v[140:141], s[44:45], 0, v[134:135]
	s_add_i32 m0, s48, 0x2000
	s_nop 0
	global_load_lds_dwordx4 v[140:141], off
	v_lshl_add_u64 v[140:141], s[46:47], 0, v[128:129]
	s_mov_b32 m0, s63
	s_nop 0
	global_load_lds_dwordx4 v[140:141], off
	v_lshl_add_u64 v[140:141], s[46:47], 0, v[132:133]
	s_mov_b32 m0, s64
	s_nop 0
	global_load_lds_dwordx4 v[140:141], off
	s_waitcnt vmcnt(8)
	s_waitcnt lgkmcnt(0)
	s_barrier
	s_setprio 1
	s_waitcnt lgkmcnt(0)
	v_mfma_f32_16x16x32_bf16 v[60:63], v[146:149], v[178:181], v[60:63]
	v_mfma_f32_16x16x32_bf16 v[56:59], v[154:157], v[178:181], v[56:59]
	v_mfma_f32_16x16x32_bf16 v[52:55], v[146:149], v[190:193], v[52:55]
	v_mfma_f32_16x16x32_bf16 v[44:47], v[154:157], v[190:193], v[44:47]
	v_mfma_f32_16x16x32_bf16 v[36:39], v[146:149], v[198:201], v[36:39]
	v_mfma_f32_16x16x32_bf16 v[28:31], v[154:157], v[198:201], v[28:31]
	v_mfma_f32_16x16x32_bf16 v[20:23], v[146:149], v[206:209], v[20:23]
	v_mfma_f32_16x16x32_bf16 v[12:15], v[154:157], v[206:209], v[12:15]
	v_mfma_f32_16x16x32_bf16 v[60:63], v[150:153], v[186:189], v[60:63]
	v_mfma_f32_16x16x32_bf16 v[56:59], v[158:161], v[186:189], v[56:59]
	v_mfma_f32_16x16x32_bf16 v[52:55], v[150:153], v[194:197], v[52:55]
	v_mfma_f32_16x16x32_bf16 v[44:47], v[158:161], v[194:197], v[44:47]
	v_mfma_f32_16x16x32_bf16 v[36:39], v[150:153], v[202:205], v[36:39]
	v_mfma_f32_16x16x32_bf16 v[28:31], v[158:161], v[202:205], v[28:31]
	v_mfma_f32_16x16x32_bf16 v[20:23], v[150:153], v[210:213], v[20:23]
	v_mfma_f32_16x16x32_bf16 v[12:15], v[158:161], v[210:213], v[12:15]
	s_setprio 0
	s_setprio 1
	v_mfma_f32_16x16x32_bf16 v[48:51], v[162:165], v[178:181], v[48:51]
	v_mfma_f32_16x16x32_bf16 v[40:43], v[170:173], v[178:181], v[40:43]
	v_mfma_f32_16x16x32_bf16 v[32:35], v[162:165], v[190:193], v[32:35]
	v_mfma_f32_16x16x32_bf16 v[24:27], v[170:173], v[190:193], v[24:27]
	v_mfma_f32_16x16x32_bf16 v[16:19], v[162:165], v[198:201], v[16:19]
	v_mfma_f32_16x16x32_bf16 v[8:11], v[170:173], v[198:201], v[8:11]
	v_mfma_f32_16x16x32_bf16 v[4:7], v[162:165], v[206:209], v[4:7]
	v_mfma_f32_16x16x32_bf16 v[0:3], v[170:173], v[206:209], v[0:3]
	v_mfma_f32_16x16x32_bf16 v[48:51], v[166:169], v[186:189], v[48:51]
	v_mfma_f32_16x16x32_bf16 v[40:43], v[174:177], v[186:189], v[40:43]
	v_mfma_f32_16x16x32_bf16 v[32:35], v[166:169], v[194:197], v[32:35]
	v_mfma_f32_16x16x32_bf16 v[24:27], v[174:177], v[194:197], v[24:27]
	v_mfma_f32_16x16x32_bf16 v[16:19], v[166:169], v[202:205], v[16:19]
	v_mfma_f32_16x16x32_bf16 v[8:11], v[174:177], v[202:205], v[8:11]
	v_mfma_f32_16x16x32_bf16 v[4:7], v[166:169], v[210:213], v[4:7]
	v_mfma_f32_16x16x32_bf16 v[0:3], v[174:177], v[210:213], v[0:3]
	s_setprio 0
	s_cmp_gt_u32 s77, 13
	s_mov_b32 s77, s78
	s_barrier
	s_cbranch_scc1 .LBB0_1000
